# attention unit prologue: counted vmcnt so only Q, bias row, K0 and V0 are awaited before tile 0; K1, V1, K2 land under the tile-0 math (second counted wait at the pre-loop barrier)
# speedup vs baseline: 1.0223x; 1.0006x over previous
.Ldk_p2:
.Lpro_nk2:
	s_add_u32 s80, s80, 0x20000
	s_addc_u32 s81, s81, 0
	s_cmp_eq_u32 s21, 0
	s_cbranch_scc1 .Lpw0
	s_cmp_gt_u32 s56, 4
	s_cbranch_scc1 .Lpw6
	s_cmp_eq_u32 s56, 0
	s_cbranch_scc1 .Lpw8
	s_waitcnt vmcnt(7)
	s_branch .Lpwd
.Lpw8:
	s_waitcnt vmcnt(8)
	s_branch .Lpwd
.Lpw6:
	s_waitcnt vmcnt(6)
	s_branch .Lpwd

.Lpwd:
	ds_write_b32 v149, v232
	s_waitcnt lgkmcnt(0)
	s_barrier



.LBB0_227:
	s_lshl_b32 s4, s59, 11
	s_and_b32 s5, s4, 0x1000000
	s_lshl_b32 s4, s36, 4
	s_and_b32 s28, s4, 0x700
	v_lshl_or_b32 v96, v148, 1, s28
	v_or_b32_e32 v96, s5, v96
	v_mov_b32_e32 v97, v209
	s_lshl_b32 s21, s21, 9
	s_mov_b32 s65, 2
	s_add_i32 s66, s8, 2
	s_mov_b32 s4, 1
	v_lshl_add_u64 v[174:175], v[170:171], 0, v[96:97]
	v_subrev_u32_e32 v204, s21, v194
	s_add_i32 s33, s61, s8
	s_mov_b32 s87, 0
	s_movk_i32 s68, 0xff00
	s_cmp_gt_u32 s56, 4
	s_cbranch_scc1 .Lqw4
	s_waitcnt vmcnt(5)
	s_branch .Lqwd
.Lqw4:
	s_waitcnt vmcnt(4)
.Lqwd:
	s_waitcnt lgkmcnt(0)
	s_barrier
	s_and_b64 vcc, exec, s[16:17]
	s_cbranch_vccz .Latt_p_qk
	s_cmp_ge_u32 s65, s66
	s_cbranch_scc1 .LBB0_228
	s_mov_b32 s5, 0
	s_mov_b32 s28, 0x12800
	s_add_i32 m0, s5, s32
	s_nop 0
	global_load_lds_dwordx4 v128, s[80:81]
	s_add_i32 m0, m0, 0x2000
	s_nop 0
	global_load_lds_dwordx4 v129, s[80:81]
	s_cmp_eq_u32 s56, 0
	s_cbranch_scc0 .Ldk_p3
	s_add_i32 m0, s5, 0x4000
	s_nop 0
	global_load_lds_dwordx4 v132, s[80:81]
